# A(1,1) next-tile stage hoisted ahead of the epilogue stores in the Z and RES GEMM instances too
# baseline (speedup 1.0000x reference)
; #define PG8_STAGE(bufoff, gbase, voff) do { _Pragma("unroll") for (int _i = 0; _i < 2; ++_i) \
;         __builtin_amdgcn_global_load_lds((const unsigned*)((const char*)(gbase) + (voff)[_i]), (LAS unsigned*)(lds + (bufoff) + ldsw + _i * 8192), 16, 0, 0); } while (0)
; #define PG8_LDA(dst, b, h) do { _Pragma("unroll") for (int m = 0; m < 4; ++m) _Pragma("unroll") for (int k = 0; k < 2; ++k) dst[m][k] = *(const LAS bf16x8*)(lds + PG8_SA(b, h) + aoff + m * 2048 + k * 1024); } while (0)
; #define PG8_LDB(dst, b, h) do { _Pragma("unroll") for (int n = 0; n < 2; ++n) _Pragma("unroll") for (int k = 0; k < 2; ++k) dst[n][k] = *(const LAS bf16x8*)(lds + PG8_SB(b, h) + boff + n * 2048 + k * 1024); } while (0)
; #define PG8_SCHED __builtin_amdgcn_sched_barrier(0)
; template <class Epi>
; __device__ __forceinline__ void gemm_phase(LAS unsigned char* lds, const Gemm g, const StaticOrder& S, const Epi& E, const int tid) {
;     ...
;         for (int t = 0; t < nt; t += 2) {
;             const bool last = (t == nt - 2);
;             const char* a1 = cA + (size_t)(t + 1) * kstep;
;             const char* a2 = last ? nA : cA + (size_t)(t + 2) * kstep; const char* b2 = last ? nB : cB + (size_t)(t + 2) * kstep;
;             const char* a3 = a2 + kstep; const char* b3 = b2 + kstep;
;             PG8_LDB(B0, 0, 0); PG8_LDB(B1, 0, 1); PG8_SCHED; PG8_LDA(At, 0, 0); PG8_STAGE(PG8_SA(1, 1), a1 + hstepA, voffA);
.LBB0_296:
	v_mov_b32_e32 v125, 0
	s_andn2_b64 vcc, exec, s[24:25]
	s_cbranch_vccnz .LBB0_300
	s_add_u32 s0, s34, 0x100
	s_addc_u32 s1, s35, 0
	s_add_u32 s6, s36, 0x80
	s_addc_u32 s7, s37, 0
	s_mov_b32 s34, 0
	s_add_i32 s36, s34, 2
	s_add_u32 s37, s6, 0x80
	s_addc_u32 s35, s7, 0
	s_add_i32 s60, 0, 0x10000
	s_cmp_eq_u32 s51, s34
	s_cselect_b32 s35, s29, s35
	s_cselect_b32 s34, s28, s37
	s_cselect_b32 s59, s31, s1
	s_cselect_b32 s58, s30, s0
	s_add_i32 s37, 0, 0x14000
	v_add_u32_e32 v142, s60, v248
	v_add_u32_e32 v158, s37, v248
	ds_read_b128 v[130:133], v142
	ds_read_b128 v[134:137], v142 offset:1024
	ds_read_b128 v[138:141], v142 offset:2048
	ds_read_b128 v[142:145], v142 offset:3072
	ds_read_b128 v[146:149], v158
	ds_read_b128 v[150:153], v158 offset:1024
	ds_read_b128 v[154:157], v158 offset:2048
	ds_read_b128 v[158:161], v158 offset:3072
	ds_read_b128 v[162:165], v194
	ds_read_b128 v[166:169], v194 offset:1024
	ds_read_b128 v[170:173], v194 offset:2048
	ds_read_b128 v[174:177], v194 offset:3072
	ds_read_b128 v[178:181], v194 offset:4096
	ds_read_b128 v[182:185], v194 offset:5120
	ds_read_b128 v[186:189], v194 offset:6144
	ds_read_b128 v[190:193], v194 offset:7168
	s_cmp_lg_u32 s53, 1
	s_cbranch_scc1 .Lkl298_nofa
	v_lshl_add_u64 v[212:213], s[6:7], 0, v[210:211]
	s_add_i32 m0, s38, 0xc000
	s_nop 0
	global_load_lds_dwordx4 v[212:213], off
	v_lshl_add_u64 v[212:213], s[6:7], 0, v[208:209]
	s_add_i32 m0, s38, 0xe000
	s_nop 0
	global_load_lds_dwordx4 v[212:213], off
.Lkl298_nofa:
	s_waitcnt vmcnt(18)
	s_waitcnt lgkmcnt(0)
	s_barrier
	s_setprio 1
	s_waitcnt lgkmcnt(0)
	v_mfma_f32_16x16x32_bf16 v[122:125], v[130:133], v[162:165], 0
	v_mfma_f32_16x16x32_bf16 v[126:129], v[138:141], v[162:165], 0
	v_mfma_f32_16x16x32_bf16 v[110:113], v[130:133], v[170:173], 0
	v_mfma_f32_16x16x32_bf16 v[106:109], v[138:141], v[170:173], 0
	v_mfma_f32_16x16x32_bf16 v[94:97], v[130:133], v[178:181], 0
	v_mfma_f32_16x16x32_bf16 v[90:93], v[138:141], v[178:181], 0
	v_mfma_f32_16x16x32_bf16 v[78:81], v[130:133], v[186:189], 0
	v_mfma_f32_16x16x32_bf16 v[74:77], v[138:141], v[186:189], 0
	v_mfma_f32_16x16x32_bf16 v[122:125], v[134:137], v[166:169], v[122:125]
	v_mfma_f32_16x16x32_bf16 v[126:129], v[142:145], v[166:169], v[126:129]
	v_mfma_f32_16x16x32_bf16 v[110:113], v[134:137], v[174:177], v[110:113]
	v_mfma_f32_16x16x32_bf16 v[106:109], v[142:145], v[174:177], v[106:109]
	v_mfma_f32_16x16x32_bf16 v[94:97], v[134:137], v[182:185], v[94:97]
	v_mfma_f32_16x16x32_bf16 v[90:93], v[142:145], v[182:185], v[90:93]
	v_mfma_f32_16x16x32_bf16 v[78:81], v[134:137], v[190:193], v[78:81]
	v_mfma_f32_16x16x32_bf16 v[74:77], v[142:145], v[190:193], v[74:77]
	s_setprio 0
	s_setprio 1
	v_mfma_f32_16x16x32_bf16 v[118:121], v[146:149], v[162:165], 0
	v_mfma_f32_16x16x32_bf16 v[114:117], v[154:157], v[162:165], 0
	v_mfma_f32_16x16x32_bf16 v[102:105], v[146:149], v[170:173], 0
	v_mfma_f32_16x16x32_bf16 v[98:101], v[154:157], v[170:173], 0
	v_mfma_f32_16x16x32_bf16 v[86:89], v[146:149], v[178:181], 0
	v_mfma_f32_16x16x32_bf16 v[82:85], v[154:157], v[178:181], 0
	v_mfma_f32_16x16x32_bf16 v[70:73], v[146:149], v[186:189], 0
	v_mfma_f32_16x16x32_bf16 v[66:69], v[154:157], v[186:189], 0
	v_mfma_f32_16x16x32_bf16 v[118:121], v[150:153], v[166:169], v[118:121]
	v_mfma_f32_16x16x32_bf16 v[114:117], v[158:161], v[166:169], v[114:117]
	v_mfma_f32_16x16x32_bf16 v[102:105], v[150:153], v[174:177], v[102:105]
	v_mfma_f32_16x16x32_bf16 v[98:101], v[158:161], v[174:177], v[98:101]
	v_mfma_f32_16x16x32_bf16 v[86:89], v[150:153], v[182:185], v[86:89]
	v_mfma_f32_16x16x32_bf16 v[82:85], v[158:161], v[182:185], v[82:85]
	v_mfma_f32_16x16x32_bf16 v[70:73], v[150:153], v[190:193], v[70:73]
	v_mfma_f32_16x16x32_bf16 v[66:69], v[158:161], v[190:193], v[66:69]
	s_setprio 0
	s_barrier
	s_add_i32 s60, s60, s11
	v_lshl_add_u64 v[212:213], s[58:59], 0, v[0:1]
	s_mov_b32 m0, s60
	ds_read_b128 v[162:165], v194 offset:16384
	ds_read_b128 v[166:169], v194 offset:17408
	ds_read_b128 v[170:173], v194 offset:18432
	ds_read_b128 v[174:177], v194 offset:19456
	ds_read_b128 v[178:181], v194 offset:20480
	ds_read_b128 v[182:185], v194 offset:21504
	ds_read_b128 v[186:189], v194 offset:22528
	ds_read_b128 v[190:193], v194 offset:23552
	global_load_lds_dwordx4 v[212:213], off
	s_add_i32 m0, s60, 0x2000
	v_lshl_add_u64 v[214:215], s[58:59], 0, v[206:207]
	s_add_u32 s58, s58, s14
	s_addc_u32 s59, s59, s15
	s_add_i32 s37, s37, s11
	global_load_lds_dwordx4 v[214:215], off
	v_lshl_add_u64 v[216:217], s[58:59], 0, v[0:1]
	s_mov_b32 m0, s37
	v_lshl_add_u64 v[218:219], s[58:59], 0, v[206:207]
	global_load_lds_dwordx4 v[216:217], off
	s_add_i32 m0, s37, 0x2000
	v_lshl_add_u64 v[220:221], s[34:35], 0, v[202:203]
	global_load_lds_dwordx4 v[218:219], off
	s_mov_b32 m0, s38
	v_lshl_add_u64 v[222:223], s[34:35], 0, v[204:205]
	global_load_lds_dwordx4 v[220:221], off
	s_mov_b32 m0, s39
	s_nop 0
	global_load_lds_dwordx4 v[222:223], off
	s_cmp_eq_u32 s53, 1
	s_cbranch_scc1 .Lkl298_w1f
	s_waitcnt vmcnt(24)
	s_branch .Lkl298_w1j

; #define PG8_STAGE(bufoff, gbase, voff) do { _Pragma("unroll") for (int _i = 0; _i < 2; ++_i) \
;         __builtin_amdgcn_global_load_lds((const unsigned*)((const char*)(gbase) + (voff)[_i]), (LAS unsigned*)(lds + (bufoff) + ldsw + _i * 8192), 16, 0, 0); } while (0)
; #define PG8_LDA(dst, b, h) do { _Pragma("unroll") for (int m = 0; m < 4; ++m) _Pragma("unroll") for (int k = 0; k < 2; ++k) dst[m][k] = *(const LAS bf16x8*)(lds + PG8_SA(b, h) + aoff + m * 2048 + k * 1024); } while (0)
; #define PG8_LDB(dst, b, h) do { _Pragma("unroll") for (int n = 0; n < 2; ++n) _Pragma("unroll") for (int k = 0; k < 2; ++k) dst[n][k] = *(const LAS bf16x8*)(lds + PG8_SB(b, h) + boff + n * 2048 + k * 1024); } while (0)
; #define PG8_MMA(ai, bj, At, Bt) do { __builtin_amdgcn_s_setprio(1); _Pragma("unroll") for (int m = 0; m < 4; ++m) _Pragma("unroll") for (int n = 0; n < 2; ++n) _Pragma("unroll") for (int k = 0; k < 2; ++k) \
;         acc[ai][bj][m][n] = __builtin_amdgcn_mfma_f32_16x16x32_bf16(Bt[n][k], At[m][k], acc[ai][bj][m][n], 0, 0, 0); __builtin_amdgcn_s_setprio(0); } while (0)
; #define PG8_WAIT_V(n) asm volatile("s_waitcnt vmcnt(" #n ")" ::: "memory")
; #define PG8_WAIT_L(n) asm volatile("s_waitcnt lgkmcnt(" #n ")" ::: "memory")
; #define PG8_BAR __builtin_amdgcn_s_barrier()
; #define PG8_SCHED __builtin_amdgcn_sched_barrier(0)
; template <class Epi>
; __device__ __forceinline__ void gemm_phase(LAS unsigned char* lds, const Gemm g, const StaticOrder& S, const Epi& E, const int tid) {
;     ...
;             PG8_WAIT_V(8); PG8_WAIT_L(0); PG8_BAR; PG8_MMA(0, 0, At, B0); PG8_MMA(0, 1, At, B1); PG8_BAR; PG8_SCHED;
;             PG8_LDA(At, 0, 1); PG8_STAGE(PG8_SB(0, 0), b2, voffB); PG8_STAGE(PG8_SB(0, 1), b2 + hstepB, voffB); PG8_STAGE(PG8_SA(0, 0), a2, voffA);
;             PG8_WAIT_V(8); PG8_WAIT_L(0); PG8_BAR; PG8_MMA(1, 0, At, B0); PG8_MMA(1, 1, At, B1); PG8_BAR; PG8_SCHED;
;             PG8_LDB(B0, 1, 0); PG8_LDB(B1, 1, 1); PG8_SCHED; PG8_LDA(At, 1, 0); PG8_STAGE(PG8_SA(0, 1), a2 + hstepA, voffA);
.Lkl298_w1j:
	s_waitcnt lgkmcnt(0)
	s_barrier
	s_setprio 1
	s_waitcnt lgkmcnt(0)
	v_mfma_f32_16x16x32_bf16 v[62:65], v[130:133], v[162:165], 0
	v_mfma_f32_16x16x32_bf16 v[58:61], v[138:141], v[162:165], 0
	v_mfma_f32_16x16x32_bf16 v[46:49], v[130:133], v[170:173], 0
	v_mfma_f32_16x16x32_bf16 v[42:45], v[138:141], v[170:173], 0
	v_mfma_f32_16x16x32_bf16 v[30:33], v[130:133], v[178:181], 0
	v_mfma_f32_16x16x32_bf16 v[26:29], v[138:141], v[178:181], 0
	v_mfma_f32_16x16x32_bf16 v[14:17], v[130:133], v[186:189], 0
	v_mfma_f32_16x16x32_bf16 v[10:13], v[138:141], v[186:189], 0
	v_mfma_f32_16x16x32_bf16 v[62:65], v[134:137], v[166:169], v[62:65]
	v_mfma_f32_16x16x32_bf16 v[58:61], v[142:145], v[166:169], v[58:61]
	v_mfma_f32_16x16x32_bf16 v[46:49], v[134:137], v[174:177], v[46:49]
	v_mfma_f32_16x16x32_bf16 v[42:45], v[142:145], v[174:177], v[42:45]
	v_mfma_f32_16x16x32_bf16 v[30:33], v[134:137], v[182:185], v[30:33]
	v_mfma_f32_16x16x32_bf16 v[26:29], v[142:145], v[182:185], v[26:29]
	v_mfma_f32_16x16x32_bf16 v[14:17], v[134:137], v[190:193], v[14:17]
	v_mfma_f32_16x16x32_bf16 v[10:13], v[142:145], v[190:193], v[10:13]
	s_setprio 0
	s_setprio 1
	v_mfma_f32_16x16x32_bf16 v[54:57], v[146:149], v[162:165], 0
	v_mfma_f32_16x16x32_bf16 v[50:53], v[154:157], v[162:165], 0
	v_mfma_f32_16x16x32_bf16 v[38:41], v[146:149], v[170:173], 0
	v_mfma_f32_16x16x32_bf16 v[34:37], v[154:157], v[170:173], 0
	v_mfma_f32_16x16x32_bf16 v[22:25], v[146:149], v[178:181], 0
	v_mfma_f32_16x16x32_bf16 v[18:21], v[154:157], v[178:181], 0
	v_mfma_f32_16x16x32_bf16 v[6:9], v[146:149], v[186:189], 0
	v_mfma_f32_16x16x32_bf16 v[2:5], v[154:157], v[186:189], 0
	v_mfma_f32_16x16x32_bf16 v[54:57], v[150:153], v[166:169], v[54:57]
	v_mfma_f32_16x16x32_bf16 v[50:53], v[158:161], v[166:169], v[50:53]
	v_mfma_f32_16x16x32_bf16 v[38:41], v[150:153], v[174:177], v[38:41]
	v_mfma_f32_16x16x32_bf16 v[34:37], v[158:161], v[174:177], v[34:37]
	v_mfma_f32_16x16x32_bf16 v[22:25], v[150:153], v[182:185], v[22:25]
	v_mfma_f32_16x16x32_bf16 v[18:21], v[158:161], v[182:185], v[18:21]
	v_mfma_f32_16x16x32_bf16 v[6:9], v[150:153], v[190:193], v[6:9]
	v_mfma_f32_16x16x32_bf16 v[2:5], v[158:161], v[190:193], v[2:5]
	s_setprio 0
	s_barrier
	s_add_i32 s37, 0, 0x18000
	s_add_i32 s58, 0, 0x1c000
	v_add_u32_e32 v142, s37, v248
	v_add_u32_e32 v158, s58, v248
	ds_read_b128 v[130:133], v142
	ds_read_b128 v[134:137], v142 offset:1024
	ds_read_b128 v[138:141], v142 offset:2048
	ds_read_b128 v[142:145], v142 offset:3072
	ds_read_b128 v[146:149], v158
	ds_read_b128 v[150:153], v158 offset:1024
	ds_read_b128 v[154:157], v158 offset:2048
	ds_read_b128 v[158:161], v158 offset:3072
	s_add_u32 s34, s34, s12
	s_addc_u32 s35, s35, s13
	s_mov_b32 m0, s43
	v_lshl_add_u64 v[224:225], s[34:35], 0, v[202:203]
	ds_read_b128 v[162:165], v194 offset:32768
	ds_read_b128 v[166:169], v194 offset:33792
	ds_read_b128 v[170:173], v194 offset:34816
	ds_read_b128 v[174:177], v194 offset:35840
	ds_read_b128 v[178:181], v194 offset:36864
	ds_read_b128 v[182:185], v194 offset:37888
	ds_read_b128 v[186:189], v194 offset:38912
	ds_read_b128 v[190:193], v194 offset:39936
	global_load_lds_dwordx4 v[224:225], off
	v_lshl_add_u64 v[224:225], s[34:35], 0, v[204:205]
	s_mov_b32 m0, s44
	s_nop 0
	global_load_lds_dwordx4 v[224:225], off
	s_cmp_eq_u32 s53, 1
	s_cbranch_scc1 .Lkl298_w2f
	s_waitcnt vmcnt(24)
	s_branch .Lkl298_w2j

; #define PG8_MMA(ai, bj, At, Bt) do { __builtin_amdgcn_s_setprio(1); _Pragma("unroll") for (int m = 0; m < 4; ++m) _Pragma("unroll") for (int n = 0; n < 2; ++n) _Pragma("unroll") for (int k = 0; k < 2; ++k) \
;         acc[ai][bj][m][n] = __builtin_amdgcn_mfma_f32_16x16x32_bf16(Bt[n][k], At[m][k], acc[ai][bj][m][n], 0, 0, 0); __builtin_amdgcn_s_setprio(0); } while (0)
; #define PG8_WAIT_V(n) asm volatile("s_waitcnt vmcnt(" #n ")" ::: "memory")
; #define PG8_WAIT_L(n) asm volatile("s_waitcnt lgkmcnt(" #n ")" ::: "memory")
; #define PG8_BAR __builtin_amdgcn_s_barrier()
; #define PG8_SCHED __builtin_amdgcn_sched_barrier(0)
; template <class Epi>
; __device__ __forceinline__ void gemm_phase(LAS unsigned char* lds, const Gemm g, const StaticOrder& S, const Epi& E, const int tid) {
;     ...
;             PG8_WAIT_V(8); PG8_WAIT_L(0); PG8_BAR; PG8_MMA(0, 0, At, B0); PG8_MMA(0, 1, At, B1); PG8_BAR; PG8_SCHED;
.Lkl298_w2j:
	s_waitcnt lgkmcnt(0)
	s_barrier
	s_setprio 1
	s_waitcnt lgkmcnt(0)
	v_mfma_f32_16x16x32_bf16 v[122:125], v[130:133], v[162:165], v[122:125]
	v_mfma_f32_16x16x32_bf16 v[126:129], v[138:141], v[162:165], v[126:129]
	v_mfma_f32_16x16x32_bf16 v[110:113], v[130:133], v[170:173], v[110:113]
	v_mfma_f32_16x16x32_bf16 v[106:109], v[138:141], v[170:173], v[106:109]
	v_mfma_f32_16x16x32_bf16 v[94:97], v[130:133], v[178:181], v[94:97]
	v_mfma_f32_16x16x32_bf16 v[90:93], v[138:141], v[178:181], v[90:93]
	v_mfma_f32_16x16x32_bf16 v[78:81], v[130:133], v[186:189], v[78:81]
	v_mfma_f32_16x16x32_bf16 v[74:77], v[138:141], v[186:189], v[74:77]
	v_mfma_f32_16x16x32_bf16 v[122:125], v[134:137], v[166:169], v[122:125]
	v_mfma_f32_16x16x32_bf16 v[126:129], v[142:145], v[166:169], v[126:129]
	v_mfma_f32_16x16x32_bf16 v[110:113], v[134:137], v[174:177], v[110:113]
	v_mfma_f32_16x16x32_bf16 v[106:109], v[142:145], v[174:177], v[106:109]
	v_mfma_f32_16x16x32_bf16 v[94:97], v[134:137], v[182:185], v[94:97]
	v_mfma_f32_16x16x32_bf16 v[90:93], v[142:145], v[182:185], v[90:93]
	v_mfma_f32_16x16x32_bf16 v[78:81], v[134:137], v[190:193], v[78:81]
	v_mfma_f32_16x16x32_bf16 v[74:77], v[142:145], v[190:193], v[74:77]
	s_setprio 0
	s_setprio 1
	v_mfma_f32_16x16x32_bf16 v[118:121], v[146:149], v[162:165], v[118:121]
	v_mfma_f32_16x16x32_bf16 v[114:117], v[154:157], v[162:165], v[114:117]
	v_mfma_f32_16x16x32_bf16 v[102:105], v[146:149], v[170:173], v[102:105]
	v_mfma_f32_16x16x32_bf16 v[98:101], v[154:157], v[170:173], v[98:101]
	v_mfma_f32_16x16x32_bf16 v[86:89], v[146:149], v[178:181], v[86:89]
	v_mfma_f32_16x16x32_bf16 v[82:85], v[154:157], v[178:181], v[82:85]
	v_mfma_f32_16x16x32_bf16 v[70:73], v[146:149], v[186:189], v[70:73]
	v_mfma_f32_16x16x32_bf16 v[66:69], v[154:157], v[186:189], v[66:69]
	v_mfma_f32_16x16x32_bf16 v[118:121], v[150:153], v[166:169], v[118:121]
	v_mfma_f32_16x16x32_bf16 v[114:117], v[158:161], v[166:169], v[114:117]
	v_mfma_f32_16x16x32_bf16 v[102:105], v[150:153], v[174:177], v[102:105]
	v_mfma_f32_16x16x32_bf16 v[98:101], v[158:161], v[174:177], v[98:101]
	v_mfma_f32_16x16x32_bf16 v[86:89], v[150:153], v[182:185], v[86:89]
	v_mfma_f32_16x16x32_bf16 v[82:85], v[158:161], v[182:185], v[82:85]
	v_mfma_f32_16x16x32_bf16 v[70:73], v[150:153], v[190:193], v[70:73]
	v_mfma_f32_16x16x32_bf16 v[66:69], v[158:161], v[190:193], v[66:69]
	s_setprio 0
	s_barrier
	s_branch .Lkl298_sp3

; #define PG8_STAGE(bufoff, gbase, voff) do { _Pragma("unroll") for (int _i = 0; _i < 2; ++_i) \
;         __builtin_amdgcn_global_load_lds((const unsigned*)((const char*)(gbase) + (voff)[_i]), (LAS unsigned*)(lds + (bufoff) + ldsw + _i * 8192), 16, 0, 0); } while (0)
; #define PG8_LDA(dst, b, h) do { _Pragma("unroll") for (int m = 0; m < 4; ++m) _Pragma("unroll") for (int k = 0; k < 2; ++k) dst[m][k] = *(const LAS bf16x8*)(lds + PG8_SA(b, h) + aoff + m * 2048 + k * 1024); } while (0)
; #define PG8_LDB(dst, b, h) do { _Pragma("unroll") for (int n = 0; n < 2; ++n) _Pragma("unroll") for (int k = 0; k < 2; ++k) dst[n][k] = *(const LAS bf16x8*)(lds + PG8_SB(b, h) + boff + n * 2048 + k * 1024); } while (0)
; #define PG8_MMA(ai, bj, At, Bt) do { __builtin_amdgcn_s_setprio(1); _Pragma("unroll") for (int m = 0; m < 4; ++m) _Pragma("unroll") for (int n = 0; n < 2; ++n) _Pragma("unroll") for (int k = 0; k < 2; ++k) \
;         acc[ai][bj][m][n] = __builtin_amdgcn_mfma_f32_16x16x32_bf16(Bt[n][k], At[m][k], acc[ai][bj][m][n], 0, 0, 0); __builtin_amdgcn_s_setprio(0); } while (0)
; #define PG8_WAIT_V(n) asm volatile("s_waitcnt vmcnt(" #n ")" ::: "memory")
; #define PG8_WAIT_L(n) asm volatile("s_waitcnt lgkmcnt(" #n ")" ::: "memory")
; #define PG8_BAR __builtin_amdgcn_s_barrier()
; #define PG8_SCHED __builtin_amdgcn_sched_barrier(0)
; template <class Epi>
; __device__ __forceinline__ void gemm_phase(LAS unsigned char* lds, const Gemm g, const StaticOrder& S, const Epi& E, const int tid) {
;     ...
;             PG8_LDB(B0, 0, 0); PG8_LDB(B1, 0, 1); PG8_SCHED; PG8_LDA(At, 0, 0); PG8_STAGE(PG8_SA(1, 1), a1 + hstepA, voffA);
;     ...
;             PG8_LDA(At, 1, 1); PG8_STAGE(PG8_SB(1, 0), b3, voffB); PG8_STAGE(PG8_SB(1, 1), b3 + hstepB, voffB); PG8_STAGE(PG8_SA(1, 0), a3, voffA);
;             PG8_WAIT_V(8); PG8_WAIT_L(0); PG8_BAR; PG8_MMA(1, 0, At, B0); PG8_MMA(1, 1, At, B1); PG8_BAR; PG8_SCHED;
;         }
;         if (wr == 0) PG8_BAR;
.Lkl298_sp3:
	s_add_i32 s34, s37, s11
	v_lshl_add_u64 v[212:213], v[212:213], 0, s[80:81]
	s_mov_b32 m0, s34
	ds_read_b128 v[162:165], v194 offset:49152
	ds_read_b128 v[166:169], v194 offset:50176
	ds_read_b128 v[170:173], v194 offset:51200
	ds_read_b128 v[174:177], v194 offset:52224
	ds_read_b128 v[178:181], v194 offset:53248
	ds_read_b128 v[182:185], v194 offset:54272
	ds_read_b128 v[186:189], v194 offset:55296
	ds_read_b128 v[190:193], v194 offset:56320
	global_load_lds_dwordx4 v[212:213], off
	v_lshl_add_u64 v[212:213], v[214:215], 0, s[80:81]
	s_add_i32 m0, s34, 0x2000
	s_add_i32 s34, s58, s11
	global_load_lds_dwordx4 v[212:213], off
	v_lshl_add_u64 v[212:213], v[216:217], 0, s[80:81]
	s_mov_b32 m0, s34
	s_nop 0
	global_load_lds_dwordx4 v[212:213], off
	v_lshl_add_u64 v[212:213], v[218:219], 0, s[80:81]
	s_add_i32 m0, s34, 0x2000
	s_nop 0
	global_load_lds_dwordx4 v[212:213], off
	v_lshl_add_u64 v[212:213], v[220:221], 0, s[80:81]
	s_mov_b32 m0, s49
	s_nop 0
	global_load_lds_dwordx4 v[212:213], off
	v_lshl_add_u64 v[212:213], v[222:223], 0, s[80:81]
	s_mov_b32 m0, s50
	s_nop 0
	global_load_lds_dwordx4 v[212:213], off
	s_waitcnt vmcnt(8)
	s_waitcnt lgkmcnt(0)
	s_barrier
	s_setprio 1
	s_waitcnt lgkmcnt(0)
	v_mfma_f32_16x16x32_bf16 v[62:65], v[130:133], v[162:165], v[62:65]
	v_mfma_f32_16x16x32_bf16 v[58:61], v[138:141], v[162:165], v[58:61]
	v_mfma_f32_16x16x32_bf16 v[46:49], v[130:133], v[170:173], v[46:49]
	v_mfma_f32_16x16x32_bf16 v[42:45], v[138:141], v[170:173], v[42:45]
	v_mfma_f32_16x16x32_bf16 v[30:33], v[130:133], v[178:181], v[30:33]
	v_mfma_f32_16x16x32_bf16 v[26:29], v[138:141], v[178:181], v[26:29]
	v_mfma_f32_16x16x32_bf16 v[14:17], v[130:133], v[186:189], v[14:17]
	v_mfma_f32_16x16x32_bf16 v[10:13], v[138:141], v[186:189], v[10:13]
	v_mfma_f32_16x16x32_bf16 v[62:65], v[134:137], v[166:169], v[62:65]
	v_mfma_f32_16x16x32_bf16 v[58:61], v[142:145], v[166:169], v[58:61]
	v_mfma_f32_16x16x32_bf16 v[46:49], v[134:137], v[174:177], v[46:49]
	v_mfma_f32_16x16x32_bf16 v[42:45], v[142:145], v[174:177], v[42:45]
	v_mfma_f32_16x16x32_bf16 v[30:33], v[134:137], v[182:185], v[30:33]
	v_mfma_f32_16x16x32_bf16 v[26:29], v[142:145], v[182:185], v[26:29]
	v_mfma_f32_16x16x32_bf16 v[14:17], v[134:137], v[190:193], v[14:17]
	v_mfma_f32_16x16x32_bf16 v[10:13], v[142:145], v[190:193], v[10:13]
	s_setprio 0
	s_setprio 1
	v_mfma_f32_16x16x32_bf16 v[54:57], v[146:149], v[162:165], v[54:57]
	v_mfma_f32_16x16x32_bf16 v[50:53], v[154:157], v[162:165], v[50:53]
	v_mfma_f32_16x16x32_bf16 v[38:41], v[146:149], v[170:173], v[38:41]
	v_mfma_f32_16x16x32_bf16 v[34:37], v[154:157], v[170:173], v[34:37]
	v_mfma_f32_16x16x32_bf16 v[22:25], v[146:149], v[178:181], v[22:25]
	v_mfma_f32_16x16x32_bf16 v[18:21], v[154:157], v[178:181], v[18:21]
	v_mfma_f32_16x16x32_bf16 v[6:9], v[146:149], v[186:189], v[6:9]
	v_mfma_f32_16x16x32_bf16 v[2:5], v[154:157], v[186:189], v[2:5]
	v_mfma_f32_16x16x32_bf16 v[54:57], v[150:153], v[166:169], v[54:57]
	v_mfma_f32_16x16x32_bf16 v[50:53], v[158:161], v[166:169], v[50:53]
	v_mfma_f32_16x16x32_bf16 v[38:41], v[150:153], v[174:177], v[38:41]
	v_mfma_f32_16x16x32_bf16 v[34:37], v[158:161], v[174:177], v[34:37]
	v_mfma_f32_16x16x32_bf16 v[22:25], v[150:153], v[182:185], v[22:25]
	v_mfma_f32_16x16x32_bf16 v[18:21], v[158:161], v[182:185], v[18:21]
	v_mfma_f32_16x16x32_bf16 v[6:9], v[150:153], v[190:193], v[6:9]
	v_mfma_f32_16x16x32_bf16 v[2:5], v[158:161], v[190:193], v[2:5]
	s_setprio 0
	s_barrier
	s_add_u32 s0, s0, 0x100
	s_addc_u32 s1, s1, 0
	s_add_u32 s6, s6, 0x100
	s_addc_u32 s7, s7, 0
	s_cmp_ge_i32 s36, s46
	s_mov_b32 s34, s36
	s_cbranch_scc0 .LBB0_298
	s_and_b64 vcc, exec, s[4:5]
	s_cbranch_vccnz .Lkl298_noa
	s_add_u32 s98, s28, 0x80
	s_addc_u32 s99, s29, 0
	v_lshl_add_u64 v[212:213], s[98:99], 0, v[210:211]
	s_add_i32 m0, s38, 0xc000
	s_nop 0
	global_load_lds_dwordx4 v[212:213], off
	v_lshl_add_u64 v[212:213], s[98:99], 0, v[208:209]
	s_add_i32 m0, s38, 0xe000
	s_nop 0
	global_load_lds_dwordx4 v[212:213], off
.Lkl298_noa:
	v_readlane_b32 s58, v254, 26
	v_readlane_b32 s59, v254, 27
	s_mov_b32 s60, 0x800000

; #define PG8_STAGE(bufoff, gbase, voff) do { _Pragma("unroll") for (int _i = 0; _i < 2; ++_i) \
;         __builtin_amdgcn_global_load_lds((const unsigned*)((const char*)(gbase) + (voff)[_i]), (LAS unsigned*)(lds + (bufoff) + ldsw + _i * 8192), 16, 0, 0); } while (0)
; #define PG8_LDA(dst, b, h) do { _Pragma("unroll") for (int m = 0; m < 4; ++m) _Pragma("unroll") for (int k = 0; k < 2; ++k) dst[m][k] = *(const LAS bf16x8*)(lds + PG8_SA(b, h) + aoff + m * 2048 + k * 1024); } while (0)
; #define PG8_LDB(dst, b, h) do { _Pragma("unroll") for (int n = 0; n < 2; ++n) _Pragma("unroll") for (int k = 0; k < 2; ++k) dst[n][k] = *(const LAS bf16x8*)(lds + PG8_SB(b, h) + boff + n * 2048 + k * 1024); } while (0)
; #define PG8_SCHED __builtin_amdgcn_sched_barrier(0)
; template <class Epi>
; __device__ __forceinline__ void gemm_phase(LAS unsigned char* lds, const Gemm g, const StaticOrder& S, const Epi& E, const int tid) {
;     ...
;         for (int t = 0; t < nt; t += 2) {
;             const bool last = (t == nt - 2);
;             const char* a1 = cA + (size_t)(t + 1) * kstep;
;             const char* a2 = last ? nA : cA + (size_t)(t + 2) * kstep; const char* b2 = last ? nB : cB + (size_t)(t + 2) * kstep;
;             const char* a3 = a2 + kstep; const char* b3 = b2 + kstep;
;             PG8_LDB(B0, 0, 0); PG8_LDB(B1, 0, 1); PG8_SCHED; PG8_LDA(At, 0, 0); PG8_STAGE(PG8_SA(1, 1), a1 + hstepA, voffA);
.LBB0_425:
	v_mov_b32_e32 v145, 0
	s_andn2_b64 vcc, exec, s[48:49]
	s_cbranch_vccnz .LBB0_428
	s_add_u32 s0, s66, 0x100
	s_addc_u32 s1, s67, 0
	s_add_u32 s6, s68, 0x80
	s_addc_u32 s7, s69, 0
	s_mov_b32 s8, 0
	s_add_i32 s10, s8, 2
	s_add_u32 s11, s6, 0x80
	s_addc_u32 s9, s7, 0
	s_add_i32 s66, 0, 0x10000
	s_cmp_eq_u32 s43, s8
	s_cselect_b32 s9, s63, s9
	s_cselect_b32 s8, s62, s11
	s_cselect_b32 s13, s65, s1
	s_cselect_b32 s12, s64, s0
	s_add_i32 s11, 0, 0x14000
	v_add_u32_e32 v78, s66, v222
	v_add_u32_e32 v168, s11, v222
	ds_read_b128 v[66:69], v78
	ds_read_b128 v[70:73], v78 offset:1024
	ds_read_b128 v[74:77], v78 offset:2048
	ds_read_b128 v[78:81], v78 offset:3072
	ds_read_b128 v[156:159], v168
	ds_read_b128 v[160:163], v168 offset:1024
	ds_read_b128 v[164:167], v168 offset:2048
	ds_read_b128 v[168:171], v168 offset:3072
	ds_read_b128 v[172:175], v223
	ds_read_b128 v[176:179], v223 offset:1024
	ds_read_b128 v[180:183], v223 offset:2048
	ds_read_b128 v[184:187], v223 offset:3072
	ds_read_b128 v[188:191], v223 offset:4096
	ds_read_b128 v[192:195], v223 offset:5120
	ds_read_b128 v[202:205], v223 offset:6144
	ds_read_b128 v[206:209], v223 offset:7168
	s_cmp_lg_u32 s42, 1
	s_cbranch_scc1 .Lkl427_nofa
	v_lshl_add_u64 v[210:211], s[6:7], 0, v[154:155]
	s_add_i32 m0, s44, 0xc000
	s_nop 0
	global_load_lds_dwordx4 v[210:211], off
	v_lshl_add_u64 v[210:211], s[6:7], 0, v[152:153]
	s_add_i32 m0, s44, 0xe000
	s_nop 0
	global_load_lds_dwordx4 v[210:211], off
.Lkl427_nofa:
	s_waitcnt vmcnt(18)
	s_waitcnt lgkmcnt(0)
	s_barrier
	s_setprio 1
	s_waitcnt lgkmcnt(0)
	v_mfma_f32_16x16x32_bf16 v[142:145], v[66:69], v[172:175], 0
	v_mfma_f32_16x16x32_bf16 v[138:141], v[74:77], v[172:175], 0
	v_mfma_f32_16x16x32_bf16 v[126:129], v[66:69], v[180:183], 0
	v_mfma_f32_16x16x32_bf16 v[122:125], v[74:77], v[180:183], 0
	v_mfma_f32_16x16x32_bf16 v[110:113], v[66:69], v[188:191], 0
	v_mfma_f32_16x16x32_bf16 v[106:109], v[74:77], v[188:191], 0
	v_mfma_f32_16x16x32_bf16 v[94:97], v[66:69], v[202:205], 0
	v_mfma_f32_16x16x32_bf16 v[90:93], v[74:77], v[202:205], 0
	v_mfma_f32_16x16x32_bf16 v[142:145], v[70:73], v[176:179], v[142:145]
	v_mfma_f32_16x16x32_bf16 v[138:141], v[78:81], v[176:179], v[138:141]
	v_mfma_f32_16x16x32_bf16 v[126:129], v[70:73], v[184:187], v[126:129]
	v_mfma_f32_16x16x32_bf16 v[122:125], v[78:81], v[184:187], v[122:125]
	v_mfma_f32_16x16x32_bf16 v[110:113], v[70:73], v[192:195], v[110:113]
	v_mfma_f32_16x16x32_bf16 v[106:109], v[78:81], v[192:195], v[106:109]
	v_mfma_f32_16x16x32_bf16 v[94:97], v[70:73], v[206:209], v[94:97]
	v_mfma_f32_16x16x32_bf16 v[90:93], v[78:81], v[206:209], v[90:93]
	s_setprio 0
	s_setprio 1
	v_mfma_f32_16x16x32_bf16 v[134:137], v[156:159], v[172:175], 0
	v_mfma_f32_16x16x32_bf16 v[130:133], v[164:167], v[172:175], 0
	v_mfma_f32_16x16x32_bf16 v[118:121], v[156:159], v[180:183], 0
	v_mfma_f32_16x16x32_bf16 v[114:117], v[164:167], v[180:183], 0
	v_mfma_f32_16x16x32_bf16 v[102:105], v[156:159], v[188:191], 0
	v_mfma_f32_16x16x32_bf16 v[98:101], v[164:167], v[188:191], 0
	v_mfma_f32_16x16x32_bf16 v[86:89], v[156:159], v[202:205], 0
	v_mfma_f32_16x16x32_bf16 v[82:85], v[164:167], v[202:205], 0
	v_mfma_f32_16x16x32_bf16 v[134:137], v[160:163], v[176:179], v[134:137]
	v_mfma_f32_16x16x32_bf16 v[130:133], v[168:171], v[176:179], v[130:133]
	v_mfma_f32_16x16x32_bf16 v[118:121], v[160:163], v[184:187], v[118:121]
	v_mfma_f32_16x16x32_bf16 v[114:117], v[168:171], v[184:187], v[114:117]
	v_mfma_f32_16x16x32_bf16 v[102:105], v[160:163], v[192:195], v[102:105]
	v_mfma_f32_16x16x32_bf16 v[98:101], v[168:171], v[192:195], v[98:101]
	v_mfma_f32_16x16x32_bf16 v[86:89], v[160:163], v[206:209], v[86:89]
	v_mfma_f32_16x16x32_bf16 v[82:85], v[168:171], v[206:209], v[82:85]
	s_setprio 0
	s_barrier
	s_add_i32 s66, s66, s85
	v_lshl_add_u64 v[210:211], s[12:13], 0, v[0:1]
	s_mov_b32 m0, s66
	ds_read_b128 v[172:175], v223 offset:16384
	ds_read_b128 v[176:179], v223 offset:17408
	ds_read_b128 v[180:183], v223 offset:18432
	ds_read_b128 v[184:187], v223 offset:19456
	ds_read_b128 v[188:191], v223 offset:20480
	ds_read_b128 v[192:195], v223 offset:21504
	ds_read_b128 v[202:205], v223 offset:22528
	ds_read_b128 v[206:209], v223 offset:23552
	global_load_lds_dwordx4 v[210:211], off
	s_add_i32 m0, s66, 0x2000
	v_lshl_add_u64 v[212:213], s[12:13], 0, v[150:151]
	s_add_u32 s12, s12, s26
	s_addc_u32 s13, s13, s27
	s_add_i32 s11, s11, s85
	global_load_lds_dwordx4 v[212:213], off
	v_lshl_add_u64 v[214:215], s[12:13], 0, v[0:1]
	s_mov_b32 m0, s11
	v_lshl_add_u64 v[216:217], s[12:13], 0, v[150:151]
	global_load_lds_dwordx4 v[214:215], off
	s_add_i32 m0, s11, 0x2000
	v_lshl_add_u64 v[218:219], s[8:9], 0, v[146:147]
	global_load_lds_dwordx4 v[216:217], off
	s_mov_b32 m0, s44
	v_lshl_add_u64 v[220:221], s[8:9], 0, v[148:149]
	global_load_lds_dwordx4 v[218:219], off
	s_mov_b32 m0, s45
	s_nop 0
	global_load_lds_dwordx4 v[220:221], off
	s_cmp_eq_u32 s42, 1
	s_cbranch_scc1 .Lkl427_w1f
	s_waitcnt vmcnt(24)
	s_branch .Lkl427_w1j

; #define PG8_STAGE(bufoff, gbase, voff) do { _Pragma("unroll") for (int _i = 0; _i < 2; ++_i) \
;         __builtin_amdgcn_global_load_lds((const unsigned*)((const char*)(gbase) + (voff)[_i]), (LAS unsigned*)(lds + (bufoff) + ldsw + _i * 8192), 16, 0, 0); } while (0)
; #define PG8_LDA(dst, b, h) do { _Pragma("unroll") for (int m = 0; m < 4; ++m) _Pragma("unroll") for (int k = 0; k < 2; ++k) dst[m][k] = *(const LAS bf16x8*)(lds + PG8_SA(b, h) + aoff + m * 2048 + k * 1024); } while (0)
; #define PG8_LDB(dst, b, h) do { _Pragma("unroll") for (int n = 0; n < 2; ++n) _Pragma("unroll") for (int k = 0; k < 2; ++k) dst[n][k] = *(const LAS bf16x8*)(lds + PG8_SB(b, h) + boff + n * 2048 + k * 1024); } while (0)
; #define PG8_MMA(ai, bj, At, Bt) do { __builtin_amdgcn_s_setprio(1); _Pragma("unroll") for (int m = 0; m < 4; ++m) _Pragma("unroll") for (int n = 0; n < 2; ++n) _Pragma("unroll") for (int k = 0; k < 2; ++k) \
;         acc[ai][bj][m][n] = __builtin_amdgcn_mfma_f32_16x16x32_bf16(Bt[n][k], At[m][k], acc[ai][bj][m][n], 0, 0, 0); __builtin_amdgcn_s_setprio(0); } while (0)
; #define PG8_WAIT_V(n) asm volatile("s_waitcnt vmcnt(" #n ")" ::: "memory")
; #define PG8_WAIT_L(n) asm volatile("s_waitcnt lgkmcnt(" #n ")" ::: "memory")
; #define PG8_BAR __builtin_amdgcn_s_barrier()
; #define PG8_SCHED __builtin_amdgcn_sched_barrier(0)
; template <class Epi>
; __device__ __forceinline__ void gemm_phase(LAS unsigned char* lds, const Gemm g, const StaticOrder& S, const Epi& E, const int tid) {
;     ...
;             PG8_WAIT_V(8); PG8_WAIT_L(0); PG8_BAR; PG8_MMA(0, 0, At, B0); PG8_MMA(0, 1, At, B1); PG8_BAR; PG8_SCHED;
;             PG8_LDA(At, 0, 1); PG8_STAGE(PG8_SB(0, 0), b2, voffB); PG8_STAGE(PG8_SB(0, 1), b2 + hstepB, voffB); PG8_STAGE(PG8_SA(0, 0), a2, voffA);
;             PG8_WAIT_V(8); PG8_WAIT_L(0); PG8_BAR; PG8_MMA(1, 0, At, B0); PG8_MMA(1, 1, At, B1); PG8_BAR; PG8_SCHED;
;             PG8_LDB(B0, 1, 0); PG8_LDB(B1, 1, 1); PG8_SCHED; PG8_LDA(At, 1, 0); PG8_STAGE(PG8_SA(0, 1), a2 + hstepA, voffA);
.Lkl427_w1j:
	s_waitcnt lgkmcnt(0)
	s_barrier
	s_setprio 1
	s_waitcnt lgkmcnt(0)
	v_mfma_f32_16x16x32_bf16 v[62:65], v[66:69], v[172:175], 0
	v_mfma_f32_16x16x32_bf16 v[58:61], v[74:77], v[172:175], 0
	v_mfma_f32_16x16x32_bf16 v[46:49], v[66:69], v[180:183], 0
	v_mfma_f32_16x16x32_bf16 v[42:45], v[74:77], v[180:183], 0
	v_mfma_f32_16x16x32_bf16 v[30:33], v[66:69], v[188:191], 0
	v_mfma_f32_16x16x32_bf16 v[26:29], v[74:77], v[188:191], 0
	v_mfma_f32_16x16x32_bf16 v[14:17], v[66:69], v[202:205], 0
	v_mfma_f32_16x16x32_bf16 v[10:13], v[74:77], v[202:205], 0
	v_mfma_f32_16x16x32_bf16 v[62:65], v[70:73], v[176:179], v[62:65]
	v_mfma_f32_16x16x32_bf16 v[58:61], v[78:81], v[176:179], v[58:61]
	v_mfma_f32_16x16x32_bf16 v[46:49], v[70:73], v[184:187], v[46:49]
	v_mfma_f32_16x16x32_bf16 v[42:45], v[78:81], v[184:187], v[42:45]
	v_mfma_f32_16x16x32_bf16 v[30:33], v[70:73], v[192:195], v[30:33]
	v_mfma_f32_16x16x32_bf16 v[26:29], v[78:81], v[192:195], v[26:29]
	v_mfma_f32_16x16x32_bf16 v[14:17], v[70:73], v[206:209], v[14:17]
	v_mfma_f32_16x16x32_bf16 v[10:13], v[78:81], v[206:209], v[10:13]
	s_setprio 0
	s_setprio 1
	v_mfma_f32_16x16x32_bf16 v[54:57], v[156:159], v[172:175], 0
	v_mfma_f32_16x16x32_bf16 v[50:53], v[164:167], v[172:175], 0
	v_mfma_f32_16x16x32_bf16 v[38:41], v[156:159], v[180:183], 0
	v_mfma_f32_16x16x32_bf16 v[34:37], v[164:167], v[180:183], 0
	v_mfma_f32_16x16x32_bf16 v[22:25], v[156:159], v[188:191], 0
	v_mfma_f32_16x16x32_bf16 v[18:21], v[164:167], v[188:191], 0
	v_mfma_f32_16x16x32_bf16 v[6:9], v[156:159], v[202:205], 0
	v_mfma_f32_16x16x32_bf16 v[2:5], v[164:167], v[202:205], 0
	v_mfma_f32_16x16x32_bf16 v[54:57], v[160:163], v[176:179], v[54:57]
	v_mfma_f32_16x16x32_bf16 v[50:53], v[168:171], v[176:179], v[50:53]
	v_mfma_f32_16x16x32_bf16 v[38:41], v[160:163], v[184:187], v[38:41]
	v_mfma_f32_16x16x32_bf16 v[34:37], v[168:171], v[184:187], v[34:37]
	v_mfma_f32_16x16x32_bf16 v[22:25], v[160:163], v[192:195], v[22:25]
	v_mfma_f32_16x16x32_bf16 v[18:21], v[168:171], v[192:195], v[18:21]
	v_mfma_f32_16x16x32_bf16 v[6:9], v[160:163], v[206:209], v[6:9]
	v_mfma_f32_16x16x32_bf16 v[2:5], v[168:171], v[206:209], v[2:5]
	s_setprio 0
	s_barrier
	s_add_i32 s11, 0, 0x18000
	s_add_i32 s12, 0, 0x1c000
	v_add_u32_e32 v78, s11, v222
	v_add_u32_e32 v168, s12, v222
	ds_read_b128 v[66:69], v78
	ds_read_b128 v[70:73], v78 offset:1024
	ds_read_b128 v[74:77], v78 offset:2048
	ds_read_b128 v[78:81], v78 offset:3072
	ds_read_b128 v[156:159], v168
	ds_read_b128 v[160:163], v168 offset:1024
	ds_read_b128 v[164:167], v168 offset:2048
	ds_read_b128 v[168:171], v168 offset:3072
	s_add_u32 s8, s8, s24
	s_addc_u32 s9, s9, s25
	s_mov_b32 m0, s52
	v_lshl_add_u64 v[224:225], s[8:9], 0, v[146:147]
	ds_read_b128 v[172:175], v223 offset:32768
	ds_read_b128 v[176:179], v223 offset:33792
	ds_read_b128 v[180:183], v223 offset:34816
	ds_read_b128 v[184:187], v223 offset:35840
	ds_read_b128 v[188:191], v223 offset:36864
	ds_read_b128 v[192:195], v223 offset:37888
	ds_read_b128 v[202:205], v223 offset:38912
	ds_read_b128 v[206:209], v223 offset:39936
	global_load_lds_dwordx4 v[224:225], off
	v_lshl_add_u64 v[224:225], s[8:9], 0, v[148:149]
	s_mov_b32 m0, s53
	s_nop 0
	global_load_lds_dwordx4 v[224:225], off
	s_cmp_eq_u32 s42, 1
	s_cbranch_scc1 .Lkl427_w2f
	s_waitcnt vmcnt(24)
	s_branch .Lkl427_w2j

; #define PG8_MMA(ai, bj, At, Bt) do { __builtin_amdgcn_s_setprio(1); _Pragma("unroll") for (int m = 0; m < 4; ++m) _Pragma("unroll") for (int n = 0; n < 2; ++n) _Pragma("unroll") for (int k = 0; k < 2; ++k) \
;         acc[ai][bj][m][n] = __builtin_amdgcn_mfma_f32_16x16x32_bf16(Bt[n][k], At[m][k], acc[ai][bj][m][n], 0, 0, 0); __builtin_amdgcn_s_setprio(0); } while (0)
; #define PG8_WAIT_V(n) asm volatile("s_waitcnt vmcnt(" #n ")" ::: "memory")
; #define PG8_WAIT_L(n) asm volatile("s_waitcnt lgkmcnt(" #n ")" ::: "memory")
; #define PG8_BAR __builtin_amdgcn_s_barrier()
; #define PG8_SCHED __builtin_amdgcn_sched_barrier(0)
; template <class Epi>
; __device__ __forceinline__ void gemm_phase(LAS unsigned char* lds, const Gemm g, const StaticOrder& S, const Epi& E, const int tid) {
;     ...
;             PG8_WAIT_V(8); PG8_WAIT_L(0); PG8_BAR; PG8_MMA(0, 0, At, B0); PG8_MMA(0, 1, At, B1); PG8_BAR; PG8_SCHED;
.Lkl427_w2j:
	s_waitcnt lgkmcnt(0)
	s_barrier
	s_setprio 1
	s_waitcnt lgkmcnt(0)
	v_mfma_f32_16x16x32_bf16 v[142:145], v[66:69], v[172:175], v[142:145]
	v_mfma_f32_16x16x32_bf16 v[138:141], v[74:77], v[172:175], v[138:141]
	v_mfma_f32_16x16x32_bf16 v[126:129], v[66:69], v[180:183], v[126:129]
	v_mfma_f32_16x16x32_bf16 v[122:125], v[74:77], v[180:183], v[122:125]
	v_mfma_f32_16x16x32_bf16 v[110:113], v[66:69], v[188:191], v[110:113]
	v_mfma_f32_16x16x32_bf16 v[106:109], v[74:77], v[188:191], v[106:109]
	v_mfma_f32_16x16x32_bf16 v[94:97], v[66:69], v[202:205], v[94:97]
	v_mfma_f32_16x16x32_bf16 v[90:93], v[74:77], v[202:205], v[90:93]
	v_mfma_f32_16x16x32_bf16 v[142:145], v[70:73], v[176:179], v[142:145]
	v_mfma_f32_16x16x32_bf16 v[138:141], v[78:81], v[176:179], v[138:141]
	v_mfma_f32_16x16x32_bf16 v[126:129], v[70:73], v[184:187], v[126:129]
	v_mfma_f32_16x16x32_bf16 v[122:125], v[78:81], v[184:187], v[122:125]
	v_mfma_f32_16x16x32_bf16 v[110:113], v[70:73], v[192:195], v[110:113]
	v_mfma_f32_16x16x32_bf16 v[106:109], v[78:81], v[192:195], v[106:109]
	v_mfma_f32_16x16x32_bf16 v[94:97], v[70:73], v[206:209], v[94:97]
	v_mfma_f32_16x16x32_bf16 v[90:93], v[78:81], v[206:209], v[90:93]
	s_setprio 0
	s_setprio 1
	v_mfma_f32_16x16x32_bf16 v[134:137], v[156:159], v[172:175], v[134:137]
	v_mfma_f32_16x16x32_bf16 v[130:133], v[164:167], v[172:175], v[130:133]
	v_mfma_f32_16x16x32_bf16 v[118:121], v[156:159], v[180:183], v[118:121]
	v_mfma_f32_16x16x32_bf16 v[114:117], v[164:167], v[180:183], v[114:117]
	v_mfma_f32_16x16x32_bf16 v[102:105], v[156:159], v[188:191], v[102:105]
	v_mfma_f32_16x16x32_bf16 v[98:101], v[164:167], v[188:191], v[98:101]
	v_mfma_f32_16x16x32_bf16 v[86:89], v[156:159], v[202:205], v[86:89]
	v_mfma_f32_16x16x32_bf16 v[82:85], v[164:167], v[202:205], v[82:85]
	v_mfma_f32_16x16x32_bf16 v[134:137], v[160:163], v[176:179], v[134:137]
	v_mfma_f32_16x16x32_bf16 v[130:133], v[168:171], v[176:179], v[130:133]
	v_mfma_f32_16x16x32_bf16 v[118:121], v[160:163], v[184:187], v[118:121]
	v_mfma_f32_16x16x32_bf16 v[114:117], v[168:171], v[184:187], v[114:117]
	v_mfma_f32_16x16x32_bf16 v[102:105], v[160:163], v[192:195], v[102:105]
	v_mfma_f32_16x16x32_bf16 v[98:101], v[168:171], v[192:195], v[98:101]
	v_mfma_f32_16x16x32_bf16 v[86:89], v[160:163], v[206:209], v[86:89]
	v_mfma_f32_16x16x32_bf16 v[82:85], v[168:171], v[206:209], v[82:85]
	s_setprio 0
	s_barrier
	s_branch .Lkl427_sp3

; #define PG8_STAGE(bufoff, gbase, voff) do { _Pragma("unroll") for (int _i = 0; _i < 2; ++_i) \
;         __builtin_amdgcn_global_load_lds((const unsigned*)((const char*)(gbase) + (voff)[_i]), (LAS unsigned*)(lds + (bufoff) + ldsw + _i * 8192), 16, 0, 0); } while (0)
; #define PG8_LDA(dst, b, h) do { _Pragma("unroll") for (int m = 0; m < 4; ++m) _Pragma("unroll") for (int k = 0; k < 2; ++k) dst[m][k] = *(const LAS bf16x8*)(lds + PG8_SA(b, h) + aoff + m * 2048 + k * 1024); } while (0)
; #define PG8_LDB(dst, b, h) do { _Pragma("unroll") for (int n = 0; n < 2; ++n) _Pragma("unroll") for (int k = 0; k < 2; ++k) dst[n][k] = *(const LAS bf16x8*)(lds + PG8_SB(b, h) + boff + n * 2048 + k * 1024); } while (0)
; #define PG8_MMA(ai, bj, At, Bt) do { __builtin_amdgcn_s_setprio(1); _Pragma("unroll") for (int m = 0; m < 4; ++m) _Pragma("unroll") for (int n = 0; n < 2; ++n) _Pragma("unroll") for (int k = 0; k < 2; ++k) \
;         acc[ai][bj][m][n] = __builtin_amdgcn_mfma_f32_16x16x32_bf16(Bt[n][k], At[m][k], acc[ai][bj][m][n], 0, 0, 0); __builtin_amdgcn_s_setprio(0); } while (0)
; #define PG8_WAIT_V(n) asm volatile("s_waitcnt vmcnt(" #n ")" ::: "memory")
; #define PG8_WAIT_L(n) asm volatile("s_waitcnt lgkmcnt(" #n ")" ::: "memory")
; #define PG8_BAR __builtin_amdgcn_s_barrier()
; #define PG8_SCHED __builtin_amdgcn_sched_barrier(0)
; template <class Epi>
; __device__ __forceinline__ void gemm_phase(LAS unsigned char* lds, const Gemm g, const StaticOrder& S, const Epi& E, const int tid) {
;     ...
;             PG8_LDB(B0, 0, 0); PG8_LDB(B1, 0, 1); PG8_SCHED; PG8_LDA(At, 0, 0); PG8_STAGE(PG8_SA(1, 1), a1 + hstepA, voffA);
;     ...
;             PG8_LDA(At, 1, 1); PG8_STAGE(PG8_SB(1, 0), b3, voffB); PG8_STAGE(PG8_SB(1, 1), b3 + hstepB, voffB); PG8_STAGE(PG8_SA(1, 0), a3, voffA);
;             PG8_WAIT_V(8); PG8_WAIT_L(0); PG8_BAR; PG8_MMA(1, 0, At, B0); PG8_MMA(1, 1, At, B1); PG8_BAR; PG8_SCHED;
;         }
;         if (wr == 0) PG8_BAR;
.Lkl427_sp3:
	s_add_i32 s8, s11, s85
	v_lshl_add_u64 v[210:211], v[210:211], 0, s[80:81]
	s_mov_b32 m0, s8
	ds_read_b128 v[172:175], v223 offset:49152
	ds_read_b128 v[176:179], v223 offset:50176
	ds_read_b128 v[180:183], v223 offset:51200
	ds_read_b128 v[184:187], v223 offset:52224
	ds_read_b128 v[188:191], v223 offset:53248
	ds_read_b128 v[192:195], v223 offset:54272
	ds_read_b128 v[202:205], v223 offset:55296
	ds_read_b128 v[206:209], v223 offset:56320
	global_load_lds_dwordx4 v[210:211], off
	v_lshl_add_u64 v[210:211], v[212:213], 0, s[80:81]
	s_add_i32 m0, s8, 0x2000
	s_add_i32 s8, s12, s85
	global_load_lds_dwordx4 v[210:211], off
	v_lshl_add_u64 v[210:211], v[214:215], 0, s[80:81]
	s_mov_b32 m0, s8
	s_nop 0
	global_load_lds_dwordx4 v[210:211], off
	v_lshl_add_u64 v[210:211], v[216:217], 0, s[80:81]
	s_add_i32 m0, s8, 0x2000
	s_nop 0
	global_load_lds_dwordx4 v[210:211], off
	v_lshl_add_u64 v[210:211], v[218:219], 0, s[80:81]
	s_mov_b32 m0, s36
	s_nop 0
	global_load_lds_dwordx4 v[210:211], off
	v_lshl_add_u64 v[210:211], v[220:221], 0, s[80:81]
	s_mov_b32 m0, s37
	s_nop 0
	global_load_lds_dwordx4 v[210:211], off
	s_waitcnt vmcnt(8)
	s_waitcnt lgkmcnt(0)
	s_barrier
	s_setprio 1
	s_waitcnt lgkmcnt(0)
	v_mfma_f32_16x16x32_bf16 v[62:65], v[66:69], v[172:175], v[62:65]
	v_mfma_f32_16x16x32_bf16 v[58:61], v[74:77], v[172:175], v[58:61]
	v_mfma_f32_16x16x32_bf16 v[46:49], v[66:69], v[180:183], v[46:49]
	v_mfma_f32_16x16x32_bf16 v[42:45], v[74:77], v[180:183], v[42:45]
	v_mfma_f32_16x16x32_bf16 v[30:33], v[66:69], v[188:191], v[30:33]
	v_mfma_f32_16x16x32_bf16 v[26:29], v[74:77], v[188:191], v[26:29]
	v_mfma_f32_16x16x32_bf16 v[14:17], v[66:69], v[202:205], v[14:17]
	v_mfma_f32_16x16x32_bf16 v[10:13], v[74:77], v[202:205], v[10:13]
	v_mfma_f32_16x16x32_bf16 v[62:65], v[70:73], v[176:179], v[62:65]
	v_mfma_f32_16x16x32_bf16 v[58:61], v[78:81], v[176:179], v[58:61]
	v_mfma_f32_16x16x32_bf16 v[46:49], v[70:73], v[184:187], v[46:49]
	v_mfma_f32_16x16x32_bf16 v[42:45], v[78:81], v[184:187], v[42:45]
	v_mfma_f32_16x16x32_bf16 v[30:33], v[70:73], v[192:195], v[30:33]
	v_mfma_f32_16x16x32_bf16 v[26:29], v[78:81], v[192:195], v[26:29]
	v_mfma_f32_16x16x32_bf16 v[14:17], v[70:73], v[206:209], v[14:17]
	v_mfma_f32_16x16x32_bf16 v[10:13], v[78:81], v[206:209], v[10:13]
	s_setprio 0
	s_setprio 1
	v_mfma_f32_16x16x32_bf16 v[54:57], v[156:159], v[172:175], v[54:57]
	v_mfma_f32_16x16x32_bf16 v[50:53], v[164:167], v[172:175], v[50:53]
	v_mfma_f32_16x16x32_bf16 v[38:41], v[156:159], v[180:183], v[38:41]
	v_mfma_f32_16x16x32_bf16 v[34:37], v[164:167], v[180:183], v[34:37]
	v_mfma_f32_16x16x32_bf16 v[22:25], v[156:159], v[188:191], v[22:25]
	v_mfma_f32_16x16x32_bf16 v[18:21], v[164:167], v[188:191], v[18:21]
	v_mfma_f32_16x16x32_bf16 v[6:9], v[156:159], v[202:205], v[6:9]
	v_mfma_f32_16x16x32_bf16 v[2:5], v[164:167], v[202:205], v[2:5]
	v_mfma_f32_16x16x32_bf16 v[54:57], v[160:163], v[176:179], v[54:57]
	v_mfma_f32_16x16x32_bf16 v[50:53], v[168:171], v[176:179], v[50:53]
	v_mfma_f32_16x16x32_bf16 v[38:41], v[160:163], v[184:187], v[38:41]
	v_mfma_f32_16x16x32_bf16 v[34:37], v[168:171], v[184:187], v[34:37]
	v_mfma_f32_16x16x32_bf16 v[22:25], v[160:163], v[192:195], v[22:25]
	v_mfma_f32_16x16x32_bf16 v[18:21], v[168:171], v[192:195], v[18:21]
	v_mfma_f32_16x16x32_bf16 v[6:9], v[160:163], v[206:209], v[6:9]
	v_mfma_f32_16x16x32_bf16 v[2:5], v[168:171], v[206:209], v[2:5]
	s_setprio 0
	s_barrier
	s_add_u32 s0, s0, 0x100
	s_addc_u32 s1, s1, 0
	s_add_u32 s6, s6, 0x100
	s_addc_u32 s7, s7, 0
	s_cmp_ge_i32 s10, s35
	s_mov_b32 s8, s10
	s_cbranch_scc0 .LBB0_427
	s_and_b64 vcc, exec, s[4:5]
	s_cbranch_vccnz .Lkl427_noa
	s_add_u32 s98, s62, 0x80
	s_addc_u32 s99, s63, 0
	v_lshl_add_u64 v[210:211], s[98:99], 0, v[154:155]
	s_add_i32 m0, s44, 0xc000
	s_nop 0
	global_load_lds_dwordx4 v[210:211], off
	v_lshl_add_u64 v[210:211], s[98:99], 0, v[152:153]
	s_add_i32 m0, s44, 0xe000
	s_nop 0
	global_load_lds_dwordx4 v[210:211], off
.Lkl427_noa:
.LBB0_428:
	s_and_b64 vcc, exec, s[50:51]
	s_cbranch_vccz .LBB0_430
	s_barrier
